# weights stored in 16x32 blocked layout so GEMM B-operand LDS-DMA reads full 128B lines
# speedup vs baseline: 1.0328x; 1.0328x over previous
.LBB0_123:
	s_or_b64 exec, exec, s[58:59]
	v_ashrrev_i32_e32 v13, 31, v12
	v_lshlrev_b64 v[12:13], 11, v[12:13]
	v_lshl_add_u64 v[12:13], s[0:1], 0, v[12:13]
	v_lshlrev_b32_e32 v0, 1, v15
	v_lshl_add_u64 v[12:13], v[12:13], 0, v[0:1]
	v_add_co_u32_e32 v12, vcc, 0x600000, v12
	v_add_u32_e32 v45, 0x100, v45
	s_nop 0
	v_addc_co_u32_e32 v13, vcc, 0, v13, vcc
	v_add_co_u32_e32 v14, vcc, 1, v14
	s_or_b64 s[56:57], vcc, s[56:57]
	v_subrev_u32_e32 v240, s94, v12
	v_bfe_u32 v241, v240, 6, 5
	v_and_b32_e32 v242, 63, v240
	v_lshl_or_b32 v242, v241, 10, v242
	v_bfe_u32 v241, v240, 11, 4
	v_lshl_or_b32 v242, v241, 6, v242
	v_and_b32_e32 v241, 0x7fff, v240
	v_sub_u32_e32 v242, v242, v241
	v_ashrrev_i32_e32 v243, 31, v242
	v_lshl_add_u64 v[240:241], v[12:13], 0, v[242:243]
	flat_store_short v[240:241], v16
	s_andn2_b64 exec, exec, s[56:57]
	s_cbranch_execz .LBB0_126

.LBB0_129:
	s_or_b64 exec, exec, s[56:57]
	v_ashrrev_i32_e32 v29, 31, v28
	v_lshlrev_b64 v[28:29], 11, v[28:29]
	v_lshl_add_u64 v[28:29], v[26:27], 0, v[28:29]
	v_add_co_u32_e32 v28, vcc, 0x600000, v28
	s_nop 1
	v_addc_co_u32_e32 v29, vcc, 0, v29, vcc
	v_cmp_lt_i32_e32 vcc, s82, v45
	s_or_b64 s[54:55], vcc, s[54:55]
	v_add_u32_e32 v45, 0x400, v45
	v_subrev_u32_e32 v240, s94, v28
	v_bfe_u32 v241, v240, 6, 5
	v_and_b32_e32 v242, 63, v240
	v_lshl_or_b32 v242, v241, 10, v242
	v_bfe_u32 v241, v240, 11, 4
	v_lshl_or_b32 v242, v241, 6, v242
	v_and_b32_e32 v241, 0x7fff, v240
	v_sub_u32_e32 v242, v242, v241
	v_ashrrev_i32_e32 v243, 31, v242
	v_lshl_add_u64 v[240:241], v[28:29], 0, v[242:243]
	flat_store_short v[240:241], v46
	s_andn2_b64 exec, exec, s[54:55]
	s_cbranch_execz .LBB0_138

.LBB0_132:
	s_or_b64 exec, exec, s[56:57]
	v_ashrrev_i32_e32 v29, 31, v28
	v_lshlrev_b64 v[28:29], 11, v[28:29]
	v_lshl_add_u64 v[28:29], v[14:15], 0, v[28:29]
	v_add_co_u32_e32 v28, vcc, 0x600000, v28
	v_add_u32_e32 v47, 0x100, v45
	s_nop 0
	v_addc_co_u32_e32 v29, vcc, 0, v29, vcc
	v_subrev_u32_e32 v240, s94, v28
	v_bfe_u32 v241, v240, 6, 5
	v_and_b32_e32 v242, 63, v240
	v_lshl_or_b32 v242, v241, 10, v242
	v_bfe_u32 v241, v240, 11, 4
	v_lshl_or_b32 v242, v241, 6, v242
	v_and_b32_e32 v241, 0x7fff, v240
	v_sub_u32_e32 v242, v242, v241
	v_ashrrev_i32_e32 v243, 31, v242
	v_lshl_add_u64 v[240:241], v[28:29], 0, v[242:243]
	flat_store_short v[240:241], v0
	v_ashrrev_i32_e32 v0, 10, v47
	v_add_u32_e32 v28, s8, v0
	v_cmp_gt_i32_e32 vcc, 32, v28
	s_and_saveexec_b64 s[56:57], vcc
	s_cbranch_execz .LBB0_134
	v_ashrrev_i32_e32 v48, 4, v28
	v_ashrrev_i32_e32 v49, 31, v48
	v_and_b32_e32 v0, 15, v28
	v_lshlrev_b64 v[48:49], 16, v[48:49]
	v_lshl_add_u64 v[48:49], v[16:17], 0, v[48:49]
	v_lshlrev_b32_e32 v0, 2, v0
	v_lshl_add_u64 v[48:49], v[48:49], 0, v[0:1]
	global_load_dword v0, v[48:49], off
	s_waitcnt vmcnt(0)
	v_cvt_pk_bf16_f32 v46, v0, s0
.LBB0_134:
	s_or_b64 exec, exec, s[56:57]
	v_ashrrev_i32_e32 v29, 31, v28
	v_lshlrev_b64 v[28:29], 11, v[28:29]
	v_lshl_add_u64 v[28:29], v[18:19], 0, v[28:29]
	v_add_co_u32_e32 v28, vcc, 0x600000, v28
	v_add_u32_e32 v47, 0x100, v47
	s_nop 0
	v_addc_co_u32_e32 v29, vcc, 0, v29, vcc
	v_ashrrev_i32_e32 v0, 10, v47
	v_subrev_u32_e32 v240, s94, v28
	v_bfe_u32 v241, v240, 6, 5
	v_and_b32_e32 v242, 63, v240
	v_lshl_or_b32 v242, v241, 10, v242
	v_bfe_u32 v241, v240, 11, 4
	v_lshl_or_b32 v242, v241, 6, v242
	v_and_b32_e32 v241, 0x7fff, v240
	v_sub_u32_e32 v242, v242, v241
	v_ashrrev_i32_e32 v243, 31, v242
	v_lshl_add_u64 v[240:241], v[28:29], 0, v[242:243]
	flat_store_short v[240:241], v46
	v_add_u32_e32 v28, s8, v0
	v_cmp_gt_i32_e32 vcc, 32, v28
	v_mov_b32_e32 v46, 0
	v_mov_b32_e32 v0, 0
	s_and_saveexec_b64 s[56:57], vcc
	s_cbranch_execz .LBB0_136
	v_ashrrev_i32_e32 v48, 4, v28
	v_ashrrev_i32_e32 v49, 31, v48
	v_and_b32_e32 v0, 15, v28
	v_lshlrev_b64 v[48:49], 16, v[48:49]
	v_lshl_add_u64 v[48:49], v[20:21], 0, v[48:49]
	v_lshlrev_b32_e32 v0, 2, v0
	v_lshl_add_u64 v[48:49], v[48:49], 0, v[0:1]
	global_load_dword v0, v[48:49], off
	s_waitcnt vmcnt(0)
	v_cvt_pk_bf16_f32 v0, v0, s0
.LBB0_136:
	s_or_b64 exec, exec, s[56:57]
	v_ashrrev_i32_e32 v29, 31, v28
	v_lshlrev_b64 v[28:29], 11, v[28:29]
	v_lshl_add_u64 v[28:29], v[22:23], 0, v[28:29]
	v_add_co_u32_e32 v28, vcc, 0x600000, v28
	s_nop 1
	v_addc_co_u32_e32 v29, vcc, 0, v29, vcc
	v_subrev_u32_e32 v240, s94, v28
	v_bfe_u32 v241, v240, 6, 5
	v_and_b32_e32 v242, 63, v240
	v_lshl_or_b32 v242, v241, 10, v242
	v_bfe_u32 v241, v240, 11, 4
	v_lshl_or_b32 v242, v241, 6, v242
	v_and_b32_e32 v241, 0x7fff, v240
	v_sub_u32_e32 v242, v242, v241
	v_ashrrev_i32_e32 v243, 31, v242
	v_lshl_add_u64 v[240:241], v[28:29], 0, v[242:243]
	flat_store_short v[240:241], v0
	v_add_u32_e32 v0, 0x100, v47
	v_ashrrev_i32_e32 v0, 10, v0
	v_add_u32_e32 v28, s8, v0
	v_cmp_gt_i32_e32 vcc, 32, v28
	s_and_saveexec_b64 s[56:57], vcc
	s_cbranch_execz .LBB0_129
	v_ashrrev_i32_e32 v46, 4, v28
	v_ashrrev_i32_e32 v47, 31, v46
	v_and_b32_e32 v0, 15, v28
	v_lshlrev_b64 v[46:47], 16, v[46:47]
	v_lshl_add_u64 v[46:47], v[24:25], 0, v[46:47]
	v_lshlrev_b32_e32 v0, 2, v0
	v_lshl_add_u64 v[46:47], v[46:47], 0, v[0:1]
	global_load_dword v0, v[46:47], off
	s_waitcnt vmcnt(0)
	v_cvt_pk_bf16_f32 v46, v0, s0
	s_branch .LBB0_129

.LBB0_142:
	ds_read2_b32 v[12:13], v36 offset1:65
	ds_read2_b32 v[14:15], v36 offset0:130 offset1:195
	v_add_u32_e32 v0, 0x400, v36
	ds_read2_b32 v[18:19], v0 offset0:134 offset1:199
	v_mov_b32_e32 v11, v1
	s_waitcnt lgkmcnt(0)
	v_cvt_pk_bf16_f32 v12, v12, v13
	v_cvt_pk_bf16_f32 v13, v14, v15
	ds_read2_b32 v[14:15], v0 offset0:4 offset1:69
	v_lshl_add_u64 v[16:17], s[48:49], 0, v[10:11]
	v_add_u32_e32 v0, 0x400, v37
	s_waitcnt lgkmcnt(0)
	v_cvt_pk_bf16_f32 v14, v14, v15
	v_cvt_pk_bf16_f32 v15, v18, v19
	v_add_u32_e32 v18, s44, v3
	v_ashrrev_i32_e32 v19, 31, v18
	v_lshlrev_b64 v[18:19], 11, v[18:19]
	v_lshl_add_u64 v[18:19], v[16:17], 0, v[18:19]
	v_subrev_u32_e32 v240, s94, v18
	v_bfe_u32 v241, v240, 6, 5
	v_and_b32_e32 v242, 63, v240
	v_lshl_or_b32 v242, v241, 10, v242
	v_bfe_u32 v241, v240, 11, 4
	v_lshl_or_b32 v242, v241, 6, v242
	v_and_b32_e32 v241, 0x7fff, v240
	v_sub_u32_e32 v242, v242, v241
	v_ashrrev_i32_e32 v243, 31, v242
	v_lshl_add_u64 v[240:241], v[18:19], 0, v[242:243]
	flat_store_dwordx4 v[240:241], v[12:15]
	ds_read2_b32 v[12:13], v37 offset1:65
	ds_read2_b32 v[14:15], v37 offset0:130 offset1:195
	ds_read2_b32 v[18:19], v0 offset0:134 offset1:199
	s_waitcnt lgkmcnt(0)
	v_cvt_pk_bf16_f32 v12, v12, v13
	v_cvt_pk_bf16_f32 v13, v14, v15
	ds_read2_b32 v[14:15], v0 offset0:4 offset1:69
	s_waitcnt lgkmcnt(0)
	v_cvt_pk_bf16_f32 v14, v14, v15
	v_cvt_pk_bf16_f32 v15, v18, v19
	v_add_u32_e32 v18, s44, v35
	v_ashrrev_i32_e32 v19, 31, v18
	v_lshlrev_b64 v[18:19], 11, v[18:19]
	v_lshl_add_u64 v[16:17], v[16:17], 0, v[18:19]
	v_subrev_u32_e32 v240, s94, v16
	v_bfe_u32 v241, v240, 6, 5
	v_and_b32_e32 v242, 63, v240
	v_lshl_or_b32 v242, v241, 10, v242
	v_bfe_u32 v241, v240, 11, 4
	v_lshl_or_b32 v242, v241, 6, v242
	v_and_b32_e32 v241, 0x7fff, v240
	v_sub_u32_e32 v242, v242, v241
	v_ashrrev_i32_e32 v243, 31, v242
	v_lshl_add_u64 v[240:241], v[16:17], 0, v[242:243]
	flat_store_dwordx4 v[240:241], v[12:15]
	s_branch .LBB0_107

.LBB0_233:
	s_and_b64 vcc, exec, s[0:1]
	s_cbranch_vccz .LBB0_279
	s_cmp_lg_u32 s13, 1
	s_cselect_b64 s[0:1], -1, 0
	s_cmp_eq_u32 s13, 1
	s_cselect_b32 s6, 32, 8
	s_cmp_lg_u32 s13, 0
	s_cselect_b64 s[22:23], -1, 0
	s_and_b64 s[4:5], s[22:23], exec
	s_cselect_b32 s21, s6, 25
	s_mul_i32 s35, s21, 0x48
	s_cmp_ge_i32 s20, s35
	s_cbranch_scc1 .LBB0_279
	s_cmp_eq_u32 s13, 2
	s_cselect_b64 s[4:5], -1, 0
	s_and_b64 s[6:7], s[4:5], exec
	s_mov_b32 s6, 0xfa00000
	s_cselect_b32 s6, s6, 0xf200000
	s_add_u32 s54, s94, s6
	s_addc_u32 s55, s95, 0
	v_readlane_b32 s7, v254, 55
	s_cmp_eq_u32 s7, 3
	s_cselect_b64 s[24:25], -1, 0
	s_waitcnt vmcnt(0)
	v_lshrrev_b32_e32 v3, 4, v134
	s_and_b64 s[26:27], s[24:25], s[4:5]
	v_sub_u32_e32 v3, 0, v3
	v_xor_b32_e32 v3, v134, v3
	s_bitcmp1_b32 s20, 8
	v_bfe_u32 v2, v134, 2, 4
	s_mov_b32 s4, 0x1fffc0
	v_lshlrev_b32_e32 v3, 4, v3
	s_cselect_b64 s[28:29], -1, 0
	s_add_u32 s38, s94, 0x4800000
	v_and_or_b32 v2, v134, s4, v2
	v_and_b32_e32 v3, 48, v3
	s_addc_u32 s39, s95, 0
	v_lshl_or_b32 v135, v2, 11, v3
	v_ashrrev_i32_e32 v2, 6, v134
	v_lshrrev_b32_e32 v5, 1, v134
	s_add_u32 s40, s94, 0x6c00000
	v_lshlrev_b32_e32 v4, 5, v2
	v_and_b32_e32 v5, 24, v5
	v_bfe_u32 v6, v134, 2, 2
	s_addc_u32 s41, s95, 0
	v_or3_b32 v4, v4, v5, v6
	s_add_u32 s42, s94, 0x2400000
	v_lshl_or_b32 v145, v4, 11, v3
	v_lshrrev_b32_e32 v5, 4, v4
	v_and_b32_e32 v6, 15, v4
	v_lshl_or_b32 v145, v5, 15, v3
	v_lshl_or_b32 v145, v6, 6, v145
	v_lshlrev_b32_e32 v4, 2, v134
	s_addc_u32 s43, s95, 0
	v_and_b32_e32 v4, 48, v4
	s_add_u32 s44, s94, 0xfc00000
	v_sub_u32_e32 v4, 0, v4
	s_addc_u32 s45, s95, 0
	v_and_b32_e32 v0, 63, v134
	v_lshlrev_b32_e32 v3, 6, v134
	v_bitop3_b32 v4, v134, 48, v4 bitop3:0x48
	s_movk_i32 s4, 0x3c0
	s_add_u32 s56, s94, 0x80
	v_lshlrev_b32_e32 v0, 4, v0
	v_and_or_b32 v4, v3, s4, v4
	v_lshlrev_b32_e32 v5, 12, v2
	s_movk_i32 s4, 0xe000
	s_addc_u32 s57, s95, 0
	v_or_b32_e32 v147, v5, v0
	v_lshl_or_b32 v148, v2, 11, v0
	v_and_or_b32 v149, v3, s4, v4
	v_and_or_b32 v0, v5, s85, v4
	s_add_u32 s58, s56, s6
	v_or_b32_e32 v142, 0x8000, v135
	v_or_b32_e32 v143, 0x10000, v135
	v_or_b32_e32 v144, 0x18000, v135
	v_or_b32_e32 v146, 0x100, v145
	v_or_b32_e32 v150, 0x4000, v0
	v_or_b32_e32 v151, 0xa000, v0
	v_add_u32_e32 v152, 0x6000, v149
	s_addc_u32 s59, s57, 0
	s_add_u32 s58, s58, 0x780
	s_addc_u32 s59, s59, 0
	s_mov_b32 s76, s20
	s_mov_b32 s77, s20
	s_branch .LBB0_237

.LBB0_242:
	s_andn2_b64 vcc, exec, s[48:49]
	s_cbranch_vccnz .LBB0_236
	s_lshl_b32 s48, s6, 8
	s_lshl_b32 s46, s80, 7
	s_ashr_i32 s49, s48, 31
	s_ashr_i32 s47, s46, 31
	s_lshl_b64 s[10:11], s[48:49], 11
	s_lshl_b64 s[50:51], s[46:47], 11
	s_add_u32 s10, s94, s10
	v_readfirstlane_b32 s5, v147
	v_add_u32_e32 v2, 0x400, v147
	s_addc_u32 s11, s95, s11
	v_mov_b32_e32 v0, v135
	s_mov_b32 m0, s5
	v_readfirstlane_b32 s5, v2
	v_add_u32_e32 v2, 0x800, v147
	v_mov_b32_e32 v130, v142
	global_load_lds_dwordx4 v0, s[10:11]
	s_mov_b32 m0, s5
	v_readfirstlane_b32 s5, v2
	v_add_u32_e32 v2, 0xc00, v147
	v_mov_b32_e32 v132, v143
	global_load_lds_dwordx4 v130, s[10:11]
	s_mov_b32 m0, s5
	v_readfirstlane_b32 s5, v2
	v_add_u32_e32 v2, 0x4000, v148
	s_add_u32 s52, s54, s50
	v_mov_b32_e32 v136, v144
	global_load_lds_dwordx4 v132, s[10:11]
	s_mov_b32 m0, s5
	v_readfirstlane_b32 s5, v2
	v_add_u32_e32 v2, 0x4400, v148
	s_addc_u32 s53, s55, s51
	v_mov_b32_e32 v138, v145
	global_load_lds_dwordx4 v136, s[10:11]
	s_mov_b32 m0, s5
	v_readfirstlane_b32 s5, v2
	v_mov_b32_e32 v140, v146
	global_load_lds_dwordx4 v138, s[52:53]
	s_mov_b32 m0, s5
	v_add_u32_e32 v4, 0x6000, v147
	v_mov_b32_e32 v131, v1
	global_load_lds_dwordx4 v140, s[52:53]
	v_readfirstlane_b32 s5, v4
	v_lshl_add_u64 v[2:3], s[10:11], 0, v[0:1]
	v_lshl_add_u64 v[2:3], v[2:3], 0, 64
	s_mov_b32 m0, s5
	v_add_u32_e32 v4, 0x6400, v147
	global_load_lds_dwordx4 v[2:3], off
	v_readfirstlane_b32 s5, v4
	v_lshl_add_u64 v[2:3], s[10:11], 0, v[130:131]
	v_lshl_add_u64 v[2:3], v[2:3], 0, 64
	s_mov_b32 m0, s5
	v_mov_b32_e32 v133, v1
	v_add_u32_e32 v4, 0x6800, v147
	global_load_lds_dwordx4 v[2:3], off
	v_readfirstlane_b32 s5, v4
	v_lshl_add_u64 v[2:3], s[10:11], 0, v[132:133]
	v_lshl_add_u64 v[2:3], v[2:3], 0, 64
	s_mov_b32 m0, s5
	v_mov_b32_e32 v137, v1
	v_add_u32_e32 v4, 0x6c00, v147
	global_load_lds_dwordx4 v[2:3], off
	v_readfirstlane_b32 s5, v4
	v_lshl_add_u64 v[2:3], s[10:11], 0, v[136:137]
	v_lshl_add_u64 v[2:3], v[2:3], 0, 64
	s_mov_b32 m0, s5
	v_mov_b32_e32 v139, v1
	v_add_u32_e32 v4, 0xa000, v148
	global_load_lds_dwordx4 v[2:3], off
	v_readfirstlane_b32 s5, v4
	v_lshl_add_u64 v[2:3], s[52:53], 0, v[138:139]
	v_lshl_add_u64 v[2:3], v[2:3], 0, s[86:87]
	s_mov_b32 m0, s5
	v_mov_b32_e32 v141, v1
	v_add_u32_e32 v4, 0xa400, v148
	global_load_lds_dwordx4 v[2:3], off
	v_readfirstlane_b32 s5, v4
	v_lshl_add_u64 v[2:3], s[52:53], 0, v[140:141]
	v_lshl_add_u64 v[2:3], v[2:3], 0, s[86:87]
	s_mov_b32 m0, s5
	s_andn2_b64 vcc, exec, s[28:29]
	global_load_lds_dwordx4 v[2:3], off
	s_cbranch_vccnz .LBB0_245
	s_sleep 10
.LBB0_245:
	s_and_b32 s9, s76, 7
	s_add_u32 s5, s58, s50
	s_addc_u32 s6, s59, s51
	s_lshl_b32 s8, s8, 3
	s_or_b32 s8, s8, s9
	s_lshl_b32 s7, s7, 3
	s_sub_i32 s7, s8, s7
	s_lshl_b32 s8, s7, 8
	s_ashr_i32 s9, s8, 31
	s_lshl_b64 s[8:9], s[8:9], 11
	s_add_u32 s8, s56, s8
	v_mov_b32_e32 v2, 0
	s_addc_u32 s9, s57, s9
	s_mov_b32 s7, 0
	s_mov_b64 s[50:51], 0
	s_mov_b32 s100, 0
	v_mov_b32_e32 v3, v2
	v_mov_b32_e32 v4, v2
	v_mov_b32_e32 v5, v2
	v_mov_b32_e32 v6, v2
	v_mov_b32_e32 v7, v2
	v_mov_b32_e32 v8, v2
	v_mov_b32_e32 v9, v2
	v_mov_b32_e32 v10, v2
	v_mov_b32_e32 v11, v2
	v_mov_b32_e32 v12, v2
	v_mov_b32_e32 v13, v2
	v_mov_b32_e32 v14, v2
	v_mov_b32_e32 v15, v2
	v_mov_b32_e32 v16, v2
	v_mov_b32_e32 v17, v2
	v_mov_b32_e32 v22, v2
	v_mov_b32_e32 v23, v2
	v_mov_b32_e32 v24, v2
	v_mov_b32_e32 v25, v2
	v_mov_b32_e32 v30, v2
	v_mov_b32_e32 v31, v2
	v_mov_b32_e32 v32, v2
	v_mov_b32_e32 v33, v2
	v_mov_b32_e32 v38, v2
	v_mov_b32_e32 v39, v2
	v_mov_b32_e32 v40, v2
	v_mov_b32_e32 v41, v2
	v_mov_b32_e32 v46, v2
	v_mov_b32_e32 v47, v2
	v_mov_b32_e32 v48, v2
	v_mov_b32_e32 v49, v2
	v_mov_b32_e32 v18, v2
	v_mov_b32_e32 v19, v2
	v_mov_b32_e32 v20, v2
	v_mov_b32_e32 v21, v2
	v_mov_b32_e32 v26, v2
	v_mov_b32_e32 v27, v2
	v_mov_b32_e32 v28, v2
	v_mov_b32_e32 v29, v2
	v_mov_b32_e32 v34, v2
	v_mov_b32_e32 v35, v2
	v_mov_b32_e32 v36, v2
	v_mov_b32_e32 v37, v2
	v_mov_b32_e32 v42, v2
	v_mov_b32_e32 v43, v2
	v_mov_b32_e32 v44, v2
	v_mov_b32_e32 v45, v2
	v_mov_b32_e32 v54, v2
	v_mov_b32_e32 v55, v2
	v_mov_b32_e32 v56, v2
	v_mov_b32_e32 v57, v2
	v_mov_b32_e32 v62, v2
	v_mov_b32_e32 v63, v2
	v_mov_b32_e32 v64, v2
	v_mov_b32_e32 v65, v2
	v_mov_b32_e32 v70, v2
	v_mov_b32_e32 v71, v2
	v_mov_b32_e32 v72, v2
	v_mov_b32_e32 v73, v2
	v_mov_b32_e32 v78, v2
	v_mov_b32_e32 v79, v2
	v_mov_b32_e32 v80, v2
	v_mov_b32_e32 v81, v2
	v_mov_b32_e32 v50, v2
	v_mov_b32_e32 v51, v2
	v_mov_b32_e32 v52, v2
	v_mov_b32_e32 v53, v2
	v_mov_b32_e32 v58, v2
	v_mov_b32_e32 v59, v2
	v_mov_b32_e32 v60, v2
	v_mov_b32_e32 v61, v2
	v_mov_b32_e32 v66, v2
	v_mov_b32_e32 v67, v2
	v_mov_b32_e32 v68, v2
	v_mov_b32_e32 v69, v2
	v_mov_b32_e32 v74, v2
	v_mov_b32_e32 v75, v2
	v_mov_b32_e32 v76, v2
	v_mov_b32_e32 v77, v2
	v_mov_b32_e32 v86, v2
	v_mov_b32_e32 v87, v2
	v_mov_b32_e32 v88, v2
	v_mov_b32_e32 v89, v2
	v_mov_b32_e32 v94, v2
	v_mov_b32_e32 v95, v2
	v_mov_b32_e32 v96, v2
	v_mov_b32_e32 v97, v2
	v_mov_b32_e32 v102, v2
	v_mov_b32_e32 v103, v2
	v_mov_b32_e32 v104, v2
	v_mov_b32_e32 v105, v2
	v_mov_b32_e32 v110, v2
	v_mov_b32_e32 v111, v2
	v_mov_b32_e32 v112, v2
	v_mov_b32_e32 v113, v2
	v_mov_b32_e32 v82, v2
	v_mov_b32_e32 v83, v2
	v_mov_b32_e32 v84, v2
	v_mov_b32_e32 v85, v2
	v_mov_b32_e32 v90, v2
	v_mov_b32_e32 v91, v2
	v_mov_b32_e32 v92, v2
	v_mov_b32_e32 v93, v2
	v_mov_b32_e32 v98, v2
	v_mov_b32_e32 v99, v2
	v_mov_b32_e32 v100, v2
	v_mov_b32_e32 v101, v2
	v_mov_b32_e32 v106, v2
	v_mov_b32_e32 v107, v2
	v_mov_b32_e32 v108, v2
	v_mov_b32_e32 v109, v2
	v_mov_b32_e32 v114, v2
	v_mov_b32_e32 v115, v2
	v_mov_b32_e32 v116, v2
	v_mov_b32_e32 v117, v2
	v_mov_b32_e32 v118, v2
	v_mov_b32_e32 v119, v2
	v_mov_b32_e32 v120, v2
	v_mov_b32_e32 v121, v2
	v_mov_b32_e32 v122, v2
	v_mov_b32_e32 v123, v2
	v_mov_b32_e32 v124, v2
	v_mov_b32_e32 v125, v2
	v_mov_b32_e32 v126, v2
	v_mov_b32_e32 v127, v2
	v_mov_b32_e32 v128, v2
	v_mov_b32_e32 v129, v2
.LBB0_246:
	s_add_i32 s10, s7, 0xffffa000
	s_cmp_lg_u32 s7, 0
	s_cselect_b32 s12, s10, 0xc000
	v_add_u32_e32 v131, s7, v150
	s_waitcnt vmcnt(6)
	s_barrier
	v_add_u32_e32 v133, s7, v149
	ds_read_b128 v[154:157], v131 offset:0
	ds_read_b128 v[158:161], v131 offset:0x400
	ds_read_b128 v[162:165], v131 offset:0x800
	ds_read_b128 v[166:169], v131 offset:0xc00
	v_add_u32_e32 v131, s12, v147
	ds_read_b128 v[170:173], v133 offset:0
	ds_read_b128 v[174:177], v133 offset:0x400
	ds_read_b128 v[178:181], v133 offset:0x800
	ds_read_b128 v[200:203], v133 offset:0xc00
	ds_read_b128 v[204:207], v133 offset:0x1000
	ds_read_b128 v[208:211], v133 offset:0x1400
	ds_read_b128 v[212:215], v133 offset:0x1800
	ds_read_b128 v[216:219], v133 offset:0x1c00
	s_add_u32 s10, s8, s50
	v_readfirstlane_b32 s13, v131
	v_add_u32_e32 v133, 0x400, v131
	s_addc_u32 s11, s9, s51
	s_mov_b32 m0, s13
	v_readfirstlane_b32 s13, v133
	v_add_u32_e32 v133, 0x800, v131
	v_add_u32_e32 v131, 0xc00, v131
	global_load_lds_dwordx4 v0, s[10:11]
	s_mov_b32 m0, s13
	v_readfirstlane_b32 s13, v133
	s_nop 0
	global_load_lds_dwordx4 v130, s[10:11]
	s_mov_b32 m0, s13
	v_readfirstlane_b32 s13, v131
	s_nop 0
	global_load_lds_dwordx4 v132, s[10:11]
	s_mov_b32 m0, s13
	s_nop 0
	global_load_lds_dwordx4 v136, s[10:11]
	s_waitcnt lgkmcnt(4)
	s_nop 0
	v_mfma_f32_16x16x32_bf16 v[126:129], v[154:157], v[170:173], v[126:129]
	v_mfma_f32_16x16x32_bf16 v[122:125], v[154:157], v[174:177], v[122:125]
	v_mfma_f32_16x16x32_bf16 v[118:121], v[154:157], v[178:181], v[118:121]
	v_mfma_f32_16x16x32_bf16 v[114:117], v[154:157], v[200:203], v[114:117]
	v_mfma_f32_16x16x32_bf16 v[110:113], v[158:161], v[170:173], v[110:113]
	v_mfma_f32_16x16x32_bf16 v[102:105], v[158:161], v[174:177], v[102:105]
	v_mfma_f32_16x16x32_bf16 v[94:97], v[158:161], v[178:181], v[94:97]
	v_mfma_f32_16x16x32_bf16 v[86:89], v[158:161], v[200:203], v[86:89]
	v_mfma_f32_16x16x32_bf16 v[78:81], v[162:165], v[170:173], v[78:81]
	v_mfma_f32_16x16x32_bf16 v[70:73], v[162:165], v[174:177], v[70:73]
	v_mfma_f32_16x16x32_bf16 v[62:65], v[162:165], v[178:181], v[62:65]
	v_mfma_f32_16x16x32_bf16 v[54:57], v[162:165], v[200:203], v[54:57]
	v_mfma_f32_16x16x32_bf16 v[46:49], v[166:169], v[170:173], v[46:49]
	v_mfma_f32_16x16x32_bf16 v[38:41], v[166:169], v[174:177], v[38:41]
	v_mfma_f32_16x16x32_bf16 v[30:33], v[166:169], v[178:181], v[30:33]
	v_mfma_f32_16x16x32_bf16 v[22:25], v[166:169], v[200:203], v[22:25]
	v_add_u32_e32 v131, s12, v148
	v_add_u32_e32 v133, 0x4000, v131
	s_add_u32 s10, s5, s100
	v_readfirstlane_b32 s12, v133
	v_add_u32_e32 v131, 0x4400, v131
	s_addc_u32 s11, s6, 0
	s_mov_b32 m0, s12
	v_readfirstlane_b32 s12, v131
	s_nop 0
	global_load_lds_dwordx4 v138, s[10:11]
	s_mov_b32 m0, s12
	s_nop 0
	global_load_lds_dwordx4 v140, s[10:11]
	s_waitcnt lgkmcnt(0)
	s_nop 0
	v_mfma_f32_16x16x32_bf16 v[106:109], v[154:157], v[204:207], v[106:109]
	v_mfma_f32_16x16x32_bf16 v[98:101], v[154:157], v[208:211], v[98:101]
	v_mfma_f32_16x16x32_bf16 v[90:93], v[154:157], v[212:215], v[90:93]
	v_mfma_f32_16x16x32_bf16 v[82:85], v[154:157], v[216:219], v[82:85]
	v_mfma_f32_16x16x32_bf16 v[74:77], v[158:161], v[204:207], v[74:77]
	v_mfma_f32_16x16x32_bf16 v[66:69], v[158:161], v[208:211], v[66:69]
	v_mfma_f32_16x16x32_bf16 v[58:61], v[158:161], v[212:215], v[58:61]
	v_mfma_f32_16x16x32_bf16 v[50:53], v[158:161], v[216:219], v[50:53]
	v_mfma_f32_16x16x32_bf16 v[42:45], v[162:165], v[204:207], v[42:45]
	v_mfma_f32_16x16x32_bf16 v[34:37], v[162:165], v[208:211], v[34:37]
	v_mfma_f32_16x16x32_bf16 v[26:29], v[162:165], v[212:215], v[26:29]
	v_mfma_f32_16x16x32_bf16 v[18:21], v[162:165], v[216:219], v[18:21]
	v_mfma_f32_16x16x32_bf16 v[14:17], v[166:169], v[204:207], v[14:17]
	v_mfma_f32_16x16x32_bf16 v[10:13], v[166:169], v[208:211], v[10:13]
	v_mfma_f32_16x16x32_bf16 v[6:9], v[166:169], v[212:215], v[6:9]
	v_mfma_f32_16x16x32_bf16 v[2:5], v[166:169], v[216:219], v[2:5]
	s_add_i32 s10, s7, 0x6000
	s_cmpk_lg_u32 s7, 0xc000
	s_cselect_b32 s7, s10, 0
	s_addk_i32 s100, 0x400
	s_add_u32 s50, s50, 64
	s_addc_u32 s51, s51, 0
	s_cmpk_lg_i32 s50, 0x780
	s_cbranch_scc1 .LBB0_246
	s_waitcnt vmcnt(6)
	s_barrier
	v_add_u32_e32 v0, s7, v150
	v_add_u32_e32 v140, s7, v149
	ds_read_b128 v[130:133], v0 offset:0
	ds_read_b128 v[136:139], v0 offset:0x400
	ds_read_b128 v[154:157], v0 offset:0x800
	ds_read_b128 v[158:161], v0 offset:0xc00
	ds_read_b128 v[162:165], v140 offset:0
	ds_read_b128 v[166:169], v140 offset:0x400
	ds_read_b128 v[170:173], v140 offset:0x800
	ds_read_b128 v[174:177], v140 offset:0xc00
	ds_read_b128 v[178:181], v140 offset:0x1000
	ds_read_b128 v[200:203], v140 offset:0x1400
	ds_read_b128 v[204:207], v140 offset:0x1800
	ds_read_b128 v[208:211], v140 offset:0x1c00
	s_lshl_b32 s49, s4, 8
	s_waitcnt lgkmcnt(4)
	s_nop 0
	v_mfma_f32_16x16x32_bf16 v[126:129], v[130:133], v[162:165], v[126:129]
	v_mfma_f32_16x16x32_bf16 v[118:121], v[130:133], v[170:173], v[118:121]
	v_mfma_f32_16x16x32_bf16 v[114:117], v[130:133], v[174:177], v[114:117]
	v_mfma_f32_16x16x32_bf16 v[110:113], v[136:139], v[162:165], v[110:113]
	v_mfma_f32_16x16x32_bf16 v[102:105], v[136:139], v[166:169], v[102:105]
	v_mfma_f32_16x16x32_bf16 v[94:97], v[136:139], v[170:173], v[94:97]
	v_mfma_f32_16x16x32_bf16 v[86:89], v[136:139], v[174:177], v[86:89]
	v_mfma_f32_16x16x32_bf16 v[70:73], v[154:157], v[166:169], v[70:73]
	v_mfma_f32_16x16x32_bf16 v[62:65], v[154:157], v[170:173], v[62:65]
	v_mfma_f32_16x16x32_bf16 v[54:57], v[154:157], v[174:177], v[54:57]
	v_mfma_f32_16x16x32_bf16 v[46:49], v[158:161], v[162:165], v[46:49]
	v_mfma_f32_16x16x32_bf16 v[38:41], v[158:161], v[166:169], v[38:41]
	v_mfma_f32_16x16x32_bf16 v[30:33], v[158:161], v[170:173], v[30:33]
	v_mfma_f32_16x16x32_bf16 v[22:25], v[158:161], v[174:177], v[22:25]
	v_mfma_f32_16x16x32_bf16 v[212:215], v[130:133], v[166:169], v[122:125]
	v_mfma_f32_16x16x32_bf16 v[216:219], v[154:157], v[162:165], v[78:81]
	s_waitcnt lgkmcnt(0)
	s_nop 0
	v_mfma_f32_16x16x32_bf16 v[174:177], v[136:139], v[178:181], v[74:77]
	v_mfma_f32_16x16x32_bf16 v[220:223], v[136:139], v[200:203], v[66:69]
	v_mfma_f32_16x16x32_bf16 v[224:227], v[136:139], v[204:207], v[58:61]
	v_mfma_f32_16x16x32_bf16 v[50:53], v[136:139], v[208:211], v[50:53]
	v_mfma_f32_16x16x32_bf16 v[136:139], v[154:157], v[178:181], v[42:45]
	v_mfma_f32_16x16x32_bf16 v[34:37], v[154:157], v[200:203], v[34:37]
	v_mfma_f32_16x16x32_bf16 v[6:9], v[158:161], v[204:207], v[6:9]
	v_mfma_f32_16x16x32_bf16 v[162:165], v[130:133], v[178:181], v[106:109]
	v_mfma_f32_16x16x32_bf16 v[166:169], v[130:133], v[200:203], v[98:101]
	v_mfma_f32_16x16x32_bf16 v[170:173], v[130:133], v[204:207], v[90:93]
	v_mfma_f32_16x16x32_bf16 v[130:133], v[130:133], v[208:211], v[82:85]
	v_mfma_f32_16x16x32_bf16 v[228:231], v[154:157], v[204:207], v[26:29]
	v_mfma_f32_16x16x32_bf16 v[154:157], v[154:157], v[208:211], v[18:21]
	v_mfma_f32_16x16x32_bf16 v[178:181], v[158:161], v[178:181], v[14:17]
	v_mfma_f32_16x16x32_bf16 v[200:203], v[158:161], v[200:203], v[10:13]
	v_mfma_f32_16x16x32_bf16 v[158:161], v[158:161], v[208:211], v[2:5]
	s_waitcnt vmcnt(0)
	s_barrier
	ds_read_b128 v[2:5], v151 offset:0
	ds_read_b128 v[14:17], v151 offset:0x400
	ds_read_b128 v[204:207], v151 offset:0x800
	ds_read_b128 v[208:211], v151 offset:0xc00
	ds_read_b128 v[10:13], v152 offset:0
	ds_read_b128 v[18:21], v152 offset:0x400
	ds_read_b128 v[26:29], v152 offset:0x800
	ds_read_b128 v[42:45], v152 offset:0xc00
	ds_read_b128 v[232:235], v152 offset:0x1000
	ds_read_b128 v[236:239], v152 offset:0x1400
	ds_read_b128 v[240:243], v152 offset:0x1800
	ds_read_b128 v[244:247], v152 offset:0x1c00
	s_nop 0
	s_waitcnt lgkmcnt(4)
	s_nop 0
	v_mfma_f32_16x16x32_bf16 v[122:125], v[2:5], v[10:13], v[126:129]
	v_mfma_f32_16x16x32_bf16 v[106:109], v[2:5], v[18:21], v[212:215]
	v_mfma_f32_16x16x32_bf16 v[90:93], v[2:5], v[26:29], v[118:121]
	v_mfma_f32_16x16x32_bf16 v[74:77], v[2:5], v[42:45], v[114:117]
	v_mfma_f32_16x16x32_bf16 v[126:129], v[14:17], v[10:13], v[110:113]
	v_mfma_f32_16x16x32_bf16 v[110:113], v[14:17], v[18:21], v[102:105]
	v_mfma_f32_16x16x32_bf16 v[94:97], v[14:17], v[26:29], v[94:97]
	v_mfma_f32_16x16x32_bf16 v[78:81], v[14:17], v[42:45], v[86:89]
	v_mfma_f32_16x16x32_bf16 v[114:117], v[204:207], v[10:13], v[216:219]
	v_mfma_f32_16x16x32_bf16 v[98:101], v[204:207], v[18:21], v[70:73]
	v_mfma_f32_16x16x32_bf16 v[82:85], v[204:207], v[26:29], v[62:65]
	v_mfma_f32_16x16x32_bf16 v[66:69], v[204:207], v[42:45], v[54:57]
	v_mfma_f32_16x16x32_bf16 v[118:121], v[208:211], v[10:13], v[46:49]
	v_mfma_f32_16x16x32_bf16 v[102:105], v[208:211], v[18:21], v[38:41]
	v_mfma_f32_16x16x32_bf16 v[86:89], v[208:211], v[26:29], v[30:33]
	v_mfma_f32_16x16x32_bf16 v[70:73], v[208:211], v[42:45], v[22:25]
	s_waitcnt lgkmcnt(0)
	s_nop 0
	v_mfma_f32_16x16x32_bf16 v[58:61], v[2:5], v[232:235], v[162:165]
	v_mfma_f32_16x16x32_bf16 v[42:45], v[2:5], v[236:239], v[166:169]
	v_mfma_f32_16x16x32_bf16 v[26:29], v[2:5], v[240:243], v[170:173]
	v_mfma_f32_16x16x32_bf16 v[10:13], v[2:5], v[244:247], v[130:133]
	v_mfma_f32_16x16x32_bf16 v[62:65], v[14:17], v[232:235], v[174:177]
	v_mfma_f32_16x16x32_bf16 v[46:49], v[14:17], v[236:239], v[220:223]
	v_mfma_f32_16x16x32_bf16 v[30:33], v[14:17], v[240:243], v[224:227]
	v_mfma_f32_16x16x32_bf16 v[14:17], v[14:17], v[244:247], v[50:53]
	v_mfma_f32_16x16x32_bf16 v[50:53], v[204:207], v[232:235], v[136:139]
	v_mfma_f32_16x16x32_bf16 v[34:37], v[204:207], v[236:239], v[34:37]
	v_mfma_f32_16x16x32_bf16 v[18:21], v[204:207], v[240:243], v[228:231]
	v_mfma_f32_16x16x32_bf16 v[2:5], v[204:207], v[244:247], v[154:157]
	v_mfma_f32_16x16x32_bf16 v[54:57], v[208:211], v[232:235], v[178:181]
	v_mfma_f32_16x16x32_bf16 v[38:41], v[208:211], v[236:239], v[200:203]
	v_mfma_f32_16x16x32_bf16 v[22:25], v[208:211], v[240:243], v[6:9]
	v_mfma_f32_16x16x32_bf16 v[6:9], v[208:211], v[244:247], v[158:161]
	v_mov_b32_e32 v136, v134
	s_mov_b64 s[50:51], -1
	s_and_b64 vcc, exec, s[22:23]
	s_barrier
	s_cbranch_vccz .LBB0_264
	s_and_b64 vcc, exec, s[0:1]
	s_cbranch_vccz .LBB0_250
	v_lshrrev_b32_e32 v0, 6, v136
	v_mul_lo_u32 v137, v0, s14
	v_and_b32_e32 v130, 15, v136
	v_and_or_b32 v0, v136, 48, v137
	s_movk_i32 s4, 0x90
	v_mad_u32_u24 v0, v130, s4, v0
	v_cvt_pk_bf16_f32 v130, v122, v123
	v_cvt_pk_bf16_f32 v131, v124, v125
	v_cvt_pk_bf16_f32 v132, v126, v127
	v_cvt_pk_bf16_f32 v133, v128, v129
	s_waitcnt vmcnt(0)
	ds_write_b128 v0, v[130:133]
	v_cvt_pk_bf16_f32 v130, v114, v115
	v_cvt_pk_bf16_f32 v131, v116, v117
	v_cvt_pk_bf16_f32 v132, v118, v119
	v_cvt_pk_bf16_f32 v133, v120, v121
	ds_write_b128 v0, v[130:133] offset:64
	v_cvt_pk_bf16_f32 v130, v106, v107
	v_cvt_pk_bf16_f32 v131, v108, v109
	v_cvt_pk_bf16_f32 v132, v110, v111
	v_cvt_pk_bf16_f32 v133, v112, v113
	ds_write_b128 v0, v[130:133] offset:2304
	v_cvt_pk_bf16_f32 v130, v98, v99
	v_cvt_pk_bf16_f32 v131, v100, v101
	v_cvt_pk_bf16_f32 v132, v102, v103
	v_cvt_pk_bf16_f32 v133, v104, v105
	ds_write_b128 v0, v[130:133] offset:2368
	v_cvt_pk_bf16_f32 v130, v90, v91
	v_cvt_pk_bf16_f32 v131, v92, v93
	v_cvt_pk_bf16_f32 v132, v94, v95
	v_cvt_pk_bf16_f32 v133, v96, v97
	ds_write_b128 v0, v[130:133] offset:4608
	v_cvt_pk_bf16_f32 v130, v82, v83
	v_cvt_pk_bf16_f32 v131, v84, v85
	v_cvt_pk_bf16_f32 v132, v86, v87
	v_cvt_pk_bf16_f32 v133, v88, v89
	ds_write_b128 v0, v[130:133] offset:4672
	v_cvt_pk_bf16_f32 v130, v74, v75
	v_cvt_pk_bf16_f32 v131, v76, v77
	v_cvt_pk_bf16_f32 v132, v78, v79
	v_cvt_pk_bf16_f32 v133, v80, v81
	ds_write_b128 v0, v[130:133] offset:6912
	v_cvt_pk_bf16_f32 v130, v66, v67
	v_cvt_pk_bf16_f32 v131, v68, v69
	v_cvt_pk_bf16_f32 v132, v70, v71
	v_cvt_pk_bf16_f32 v133, v72, v73
	ds_write_b128 v0, v[130:133] offset:6976
	v_cvt_pk_bf16_f32 v130, v58, v59
	v_cvt_pk_bf16_f32 v131, v60, v61
	v_cvt_pk_bf16_f32 v132, v62, v63
	v_cvt_pk_bf16_f32 v133, v64, v65
	ds_write_b128 v0, v[130:133] offset:9216
	v_cvt_pk_bf16_f32 v130, v50, v51
	v_cvt_pk_bf16_f32 v131, v52, v53
	v_cvt_pk_bf16_f32 v132, v54, v55
	v_cvt_pk_bf16_f32 v133, v56, v57
	ds_write_b128 v0, v[130:133] offset:9280
	v_cvt_pk_bf16_f32 v130, v42, v43
	v_cvt_pk_bf16_f32 v131, v44, v45
	v_cvt_pk_bf16_f32 v132, v46, v47
	v_cvt_pk_bf16_f32 v133, v48, v49
	ds_write_b128 v0, v[130:133] offset:11520
	v_cvt_pk_bf16_f32 v130, v34, v35
	v_cvt_pk_bf16_f32 v131, v36, v37
	v_cvt_pk_bf16_f32 v132, v38, v39
	v_cvt_pk_bf16_f32 v133, v40, v41
	ds_write_b128 v0, v[130:133] offset:11584
	v_cvt_pk_bf16_f32 v130, v26, v27
	v_cvt_pk_bf16_f32 v131, v28, v29
	v_cvt_pk_bf16_f32 v132, v30, v31
	v_cvt_pk_bf16_f32 v133, v32, v33
	ds_write_b128 v0, v[130:133] offset:13824
	v_cvt_pk_bf16_f32 v130, v18, v19
	v_cvt_pk_bf16_f32 v131, v20, v21
	v_cvt_pk_bf16_f32 v132, v22, v23
	v_cvt_pk_bf16_f32 v133, v24, v25
	ds_write_b128 v0, v[130:133] offset:13888
	v_cvt_pk_bf16_f32 v130, v10, v11
	v_cvt_pk_bf16_f32 v131, v12, v13
	v_cvt_pk_bf16_f32 v132, v14, v15
	v_cvt_pk_bf16_f32 v133, v16, v17
	ds_write_b128 v0, v[130:133] offset:16128
	v_cvt_pk_bf16_f32 v130, v2, v3
	v_cvt_pk_bf16_f32 v131, v4, v5
	v_cvt_pk_bf16_f32 v132, v6, v7
	v_cvt_pk_bf16_f32 v133, v8, v9
	ds_write_b128 v0, v[130:133] offset:16192
	v_and_b32_e32 v0, 0xffffff80, v136
	v_add_u32_e32 v130, s48, v0
	v_ashrrev_i32_e32 v131, 31, v130
	v_lshlrev_b64 v[130:131], 11, v[130:131]
	v_lshl_add_u64 v[130:131], s[38:39], 0, v[130:131]
	v_and_b32_e32 v0, 64, v136
	v_lshl_add_u64 v[130:131], s[46:47], 1, v[130:131]
	v_lshlrev_b32_e32 v0, 1, v0
	v_lshl_add_u64 v[138:139], v[130:131], 0, v[0:1]
	v_lshlrev_b32_e32 v0, 4, v136
	v_and_b32_e32 v0, 0x70, v0
	v_bfe_u32 v140, v136, 3, 3
	v_or_b32_e32 v130, v137, v0
	s_waitcnt lgkmcnt(0)
	v_mad_u32_u24 v137, v140, s4, v130
	ds_read_b128 v[130:133], v137
	v_lshl_add_u64 v[138:139], v[138:139], 0, v[0:1]
	v_lshlrev_b32_e32 v0, 11, v140
	v_lshl_add_u64 v[140:141], v[138:139], 0, v[0:1]
	s_mov_b64 s[50:51], 0
	s_waitcnt lgkmcnt(0)
	flat_store_dwordx4 v[140:141], v[130:133]
	ds_read_b128 v[130:133], v137 offset:1152
	v_or_b32_e32 v140, 0x4000, v0
	v_mov_b32_e32 v141, v1
	v_lshl_add_u64 v[140:141], v[138:139], 0, v[140:141]
	s_waitcnt lgkmcnt(0)
	flat_store_dwordx4 v[140:141], v[130:133]
	ds_read_b128 v[130:133], v137 offset:2304
	v_or_b32_e32 v140, 0x8000, v0
	v_mov_b32_e32 v141, v1
	v_lshl_add_u64 v[140:141], v[138:139], 0, v[140:141]
	s_waitcnt lgkmcnt(0)
	flat_store_dwordx4 v[140:141], v[130:133]
	ds_read_b128 v[130:133], v137 offset:3456
	v_or_b32_e32 v140, 0xc000, v0
	v_mov_b32_e32 v141, v1
	v_lshl_add_u64 v[140:141], v[138:139], 0, v[140:141]
	s_waitcnt lgkmcnt(0)
	flat_store_dwordx4 v[140:141], v[130:133]
	ds_read_b128 v[130:133], v137 offset:4608
	v_or_b32_e32 v140, 0x10000, v0
	v_mov_b32_e32 v141, v1
	v_lshl_add_u64 v[140:141], v[138:139], 0, v[140:141]
	s_waitcnt lgkmcnt(0)
	flat_store_dwordx4 v[140:141], v[130:133]
	ds_read_b128 v[130:133], v137 offset:5760
	v_or_b32_e32 v140, 0x14000, v0
	v_mov_b32_e32 v141, v1
	v_lshl_add_u64 v[140:141], v[138:139], 0, v[140:141]
	s_waitcnt lgkmcnt(0)
	flat_store_dwordx4 v[140:141], v[130:133]
	ds_read_b128 v[130:133], v137 offset:6912
	v_or_b32_e32 v140, 0x18000, v0
	v_mov_b32_e32 v141, v1
	v_lshl_add_u64 v[140:141], v[138:139], 0, v[140:141]
	s_waitcnt lgkmcnt(0)
	flat_store_dwordx4 v[140:141], v[130:133]
	ds_read_b128 v[130:133], v137 offset:8064
	v_or_b32_e32 v140, 0x1c000, v0
	v_mov_b32_e32 v141, v1
	v_lshl_add_u64 v[140:141], v[138:139], 0, v[140:141]
	s_waitcnt lgkmcnt(0)
	flat_store_dwordx4 v[140:141], v[130:133]
	ds_read_b128 v[130:133], v137 offset:9216
	v_or_b32_e32 v140, 0x20000, v0
	v_mov_b32_e32 v141, v1
	v_lshl_add_u64 v[140:141], v[138:139], 0, v[140:141]
	s_waitcnt lgkmcnt(0)
	flat_store_dwordx4 v[140:141], v[130:133]
	ds_read_b128 v[130:133], v137 offset:10368
	v_or_b32_e32 v140, 0x24000, v0
	v_mov_b32_e32 v141, v1
	v_lshl_add_u64 v[140:141], v[138:139], 0, v[140:141]
	s_waitcnt lgkmcnt(0)
	flat_store_dwordx4 v[140:141], v[130:133]
	ds_read_b128 v[130:133], v137 offset:11520
	v_or_b32_e32 v140, 0x28000, v0
	v_mov_b32_e32 v141, v1
	v_lshl_add_u64 v[140:141], v[138:139], 0, v[140:141]
	s_waitcnt lgkmcnt(0)
	flat_store_dwordx4 v[140:141], v[130:133]
	ds_read_b128 v[130:133], v137 offset:12672
	v_or_b32_e32 v140, 0x2c000, v0
	v_mov_b32_e32 v141, v1
	v_lshl_add_u64 v[140:141], v[138:139], 0, v[140:141]
	s_waitcnt lgkmcnt(0)
	flat_store_dwordx4 v[140:141], v[130:133]
	ds_read_b128 v[130:133], v137 offset:13824
	v_or_b32_e32 v140, 0x30000, v0
	v_mov_b32_e32 v141, v1
	v_lshl_add_u64 v[140:141], v[138:139], 0, v[140:141]
	s_waitcnt lgkmcnt(0)
	flat_store_dwordx4 v[140:141], v[130:133]
	ds_read_b128 v[130:133], v137 offset:14976
	v_or_b32_e32 v140, 0x34000, v0
	v_mov_b32_e32 v141, v1
	v_lshl_add_u64 v[140:141], v[138:139], 0, v[140:141]
	s_waitcnt lgkmcnt(0)
	flat_store_dwordx4 v[140:141], v[130:133]
	ds_read_b128 v[130:133], v137 offset:16128
	v_or_b32_e32 v140, 0x38000, v0
	v_mov_b32_e32 v141, v1
	v_lshl_add_u64 v[140:141], v[138:139], 0, v[140:141]
	v_or_b32_e32 v0, 0x3c000, v0
	s_waitcnt lgkmcnt(0)
	flat_store_dwordx4 v[140:141], v[130:133]
	ds_read_b128 v[130:133], v137 offset:17280
	v_lshl_add_u64 v[138:139], v[138:139], 0, v[0:1]
	s_waitcnt lgkmcnt(0)
	flat_store_dwordx4 v[138:139], v[130:133]
	s_waitcnt lgkmcnt(0)
	s_barrier

.LBB0_301:
	s_or_b64 exec, exec, s[54:55]
	v_ashrrev_i32_e32 v3, 31, v2
	v_lshlrev_b64 v[2:3], 11, v[2:3]
	v_lshl_add_u64 v[2:3], s[0:1], 0, v[2:3]
	v_lshlrev_b32_e32 v0, 1, v5
	v_lshl_add_u64 v[2:3], v[2:3], 0, v[0:1]
	v_add_co_u32_e32 v2, vcc, 0x600000, v2
	v_add_u32_e32 v20, 0x100, v20
	s_nop 0
	v_addc_co_u32_e32 v3, vcc, 0, v3, vcc
	v_add_co_u32_e32 v4, vcc, 1, v4
	s_or_b64 s[52:53], vcc, s[52:53]
	v_subrev_u32_e32 v240, s94, v2
	v_bfe_u32 v241, v240, 6, 5
	v_and_b32_e32 v242, 63, v240
	v_lshl_or_b32 v242, v241, 10, v242
	v_bfe_u32 v241, v240, 11, 4
	v_lshl_or_b32 v242, v241, 6, v242
	v_and_b32_e32 v241, 0x7fff, v240
	v_sub_u32_e32 v242, v242, v241
	v_ashrrev_i32_e32 v243, 31, v242
	v_lshl_add_u64 v[240:241], v[2:3], 0, v[242:243]
	flat_store_short v[240:241], v6
	s_andn2_b64 exec, exec, s[52:53]
	s_cbranch_execz .LBB0_304

.LBB0_307:
	s_or_b64 exec, exec, s[52:53]
	v_ashrrev_i32_e32 v19, 31, v18
	v_lshlrev_b64 v[18:19], 11, v[18:19]
	v_lshl_add_u64 v[18:19], v[16:17], 0, v[18:19]
	v_add_co_u32_e32 v18, vcc, 0x600000, v18
	s_nop 1
	v_addc_co_u32_e32 v19, vcc, 0, v19, vcc
	v_cmp_lt_i32_e32 vcc, s82, v20
	s_or_b64 s[50:51], vcc, s[50:51]
	v_add_u32_e32 v20, 0x400, v20
	v_subrev_u32_e32 v240, s94, v18
	v_bfe_u32 v241, v240, 6, 5
	v_and_b32_e32 v242, 63, v240
	v_lshl_or_b32 v242, v241, 10, v242
	v_bfe_u32 v241, v240, 11, 4
	v_lshl_or_b32 v242, v241, 6, v242
	v_and_b32_e32 v241, 0x7fff, v240
	v_sub_u32_e32 v242, v242, v241
	v_ashrrev_i32_e32 v243, 31, v242
	v_lshl_add_u64 v[240:241], v[18:19], 0, v[242:243]
	flat_store_short v[240:241], v21
	s_andn2_b64 exec, exec, s[50:51]
	s_cbranch_execz .LBB0_316

.LBB0_310:
	s_or_b64 exec, exec, s[52:53]
	v_ashrrev_i32_e32 v19, 31, v18
	v_lshlrev_b64 v[18:19], 11, v[18:19]
	v_lshl_add_u64 v[18:19], v[4:5], 0, v[18:19]
	v_add_co_u32_e32 v18, vcc, 0x600000, v18
	v_add_u32_e32 v22, 0x100, v20
	s_nop 0
	v_addc_co_u32_e32 v19, vcc, 0, v19, vcc
	v_subrev_u32_e32 v240, s94, v18
	v_bfe_u32 v241, v240, 6, 5
	v_and_b32_e32 v242, 63, v240
	v_lshl_or_b32 v242, v241, 10, v242
	v_bfe_u32 v241, v240, 11, 4
	v_lshl_or_b32 v242, v241, 6, v242
	v_and_b32_e32 v241, 0x7fff, v240
	v_sub_u32_e32 v242, v242, v241
	v_ashrrev_i32_e32 v243, 31, v242
	v_lshl_add_u64 v[240:241], v[18:19], 0, v[242:243]
	flat_store_short v[240:241], v0
	v_ashrrev_i32_e32 v0, 10, v22
	v_add_u32_e32 v18, s6, v0
	v_cmp_gt_i32_e32 vcc, 32, v18
	s_and_saveexec_b64 s[52:53], vcc
	s_cbranch_execz .LBB0_312
	v_ashrrev_i32_e32 v24, 4, v18
	v_ashrrev_i32_e32 v25, 31, v24
	v_and_b32_e32 v0, 15, v18
	v_lshlrev_b64 v[24:25], 16, v[24:25]
	v_lshl_add_u64 v[24:25], v[6:7], 0, v[24:25]
	v_lshlrev_b32_e32 v0, 2, v0
	v_lshl_add_u64 v[24:25], v[24:25], 0, v[0:1]
	global_load_dword v0, v[24:25], off
	s_waitcnt vmcnt(0)
	v_cvt_pk_bf16_f32 v21, v0, s0
.LBB0_312:
	s_or_b64 exec, exec, s[52:53]
	v_ashrrev_i32_e32 v19, 31, v18
	v_lshlrev_b64 v[18:19], 11, v[18:19]
	v_lshl_add_u64 v[18:19], v[8:9], 0, v[18:19]
	v_add_co_u32_e32 v18, vcc, 0x600000, v18
	v_add_u32_e32 v22, 0x100, v22
	s_nop 0
	v_addc_co_u32_e32 v19, vcc, 0, v19, vcc
	v_ashrrev_i32_e32 v0, 10, v22
	v_subrev_u32_e32 v240, s94, v18
	v_bfe_u32 v241, v240, 6, 5
	v_and_b32_e32 v242, 63, v240
	v_lshl_or_b32 v242, v241, 10, v242
	v_bfe_u32 v241, v240, 11, 4
	v_lshl_or_b32 v242, v241, 6, v242
	v_and_b32_e32 v241, 0x7fff, v240
	v_sub_u32_e32 v242, v242, v241
	v_ashrrev_i32_e32 v243, 31, v242
	v_lshl_add_u64 v[240:241], v[18:19], 0, v[242:243]
	flat_store_short v[240:241], v21
	v_add_u32_e32 v18, s6, v0
	v_cmp_gt_i32_e32 vcc, 32, v18
	v_mov_b32_e32 v21, 0
	v_mov_b32_e32 v0, 0
	s_and_saveexec_b64 s[52:53], vcc
	s_cbranch_execz .LBB0_314
	v_ashrrev_i32_e32 v24, 4, v18
	v_ashrrev_i32_e32 v25, 31, v24
	v_and_b32_e32 v0, 15, v18
	v_lshlrev_b64 v[24:25], 16, v[24:25]
	v_lshl_add_u64 v[24:25], v[10:11], 0, v[24:25]
	v_lshlrev_b32_e32 v0, 2, v0
	v_lshl_add_u64 v[24:25], v[24:25], 0, v[0:1]
	global_load_dword v0, v[24:25], off
	s_waitcnt vmcnt(0)
	v_cvt_pk_bf16_f32 v0, v0, s0
.LBB0_314:
	s_or_b64 exec, exec, s[52:53]
	v_ashrrev_i32_e32 v19, 31, v18
	v_lshlrev_b64 v[18:19], 11, v[18:19]
	v_lshl_add_u64 v[18:19], v[12:13], 0, v[18:19]
	v_add_co_u32_e32 v18, vcc, 0x600000, v18
	s_nop 1
	v_addc_co_u32_e32 v19, vcc, 0, v19, vcc
	v_subrev_u32_e32 v240, s94, v18
	v_bfe_u32 v241, v240, 6, 5
	v_and_b32_e32 v242, 63, v240
	v_lshl_or_b32 v242, v241, 10, v242
	v_bfe_u32 v241, v240, 11, 4
	v_lshl_or_b32 v242, v241, 6, v242
	v_and_b32_e32 v241, 0x7fff, v240
	v_sub_u32_e32 v242, v242, v241
	v_ashrrev_i32_e32 v243, 31, v242
	v_lshl_add_u64 v[240:241], v[18:19], 0, v[242:243]
	flat_store_short v[240:241], v0
	v_add_u32_e32 v0, 0x100, v22
	v_ashrrev_i32_e32 v0, 10, v0
	v_add_u32_e32 v18, s6, v0
	v_cmp_gt_i32_e32 vcc, 32, v18
	s_and_saveexec_b64 s[52:53], vcc
	s_cbranch_execz .LBB0_307
	v_ashrrev_i32_e32 v22, 4, v18
	v_ashrrev_i32_e32 v23, 31, v22
	v_and_b32_e32 v0, 15, v18
	v_lshlrev_b64 v[22:23], 16, v[22:23]
	v_lshl_add_u64 v[22:23], v[14:15], 0, v[22:23]
	v_lshlrev_b32_e32 v0, 2, v0
	v_lshl_add_u64 v[22:23], v[22:23], 0, v[0:1]
	global_load_dword v0, v[22:23], off
	s_waitcnt vmcnt(0)
	v_cvt_pk_bf16_f32 v21, v0, s0
	s_branch .LBB0_307

.LBB0_319:
	s_andn2_b64 vcc, exec, s[26:27]
	s_cbranch_vccnz .LBB0_321
	ds_read2_b32 v[2:3], v39 offset1:65
	ds_read2_b32 v[4:5], v39 offset0:130 offset1:195
	v_add_u32_e32 v0, 0x400, v39
	ds_read2_b32 v[8:9], v0 offset0:134 offset1:199
	v_mov_b32_e32 v109, v1
	s_waitcnt lgkmcnt(0)
	v_cvt_pk_bf16_f32 v2, v2, v3
	v_cvt_pk_bf16_f32 v3, v4, v5
	ds_read2_b32 v[4:5], v0 offset0:4 offset1:69
	v_lshl_add_u64 v[6:7], s[24:25], 0, v[108:109]
	v_add_u32_e32 v0, 0x400, v162
	s_waitcnt lgkmcnt(0)
	v_cvt_pk_bf16_f32 v4, v4, v5
	v_cvt_pk_bf16_f32 v5, v8, v9
	v_add_u32_e32 v8, s4, v153
	v_ashrrev_i32_e32 v9, 31, v8
	v_lshlrev_b64 v[8:9], 11, v[8:9]
	v_lshl_add_u64 v[8:9], v[6:7], 0, v[8:9]
	v_subrev_u32_e32 v240, s94, v8
	v_bfe_u32 v241, v240, 6, 5
	v_and_b32_e32 v242, 63, v240
	v_lshl_or_b32 v242, v241, 10, v242
	v_bfe_u32 v241, v240, 11, 4
	v_lshl_or_b32 v242, v241, 6, v242
	v_and_b32_e32 v241, 0x7fff, v240
	v_sub_u32_e32 v242, v242, v241
	v_ashrrev_i32_e32 v243, 31, v242
	v_lshl_add_u64 v[240:241], v[8:9], 0, v[242:243]
	flat_store_dwordx4 v[240:241], v[2:5]
	ds_read2_b32 v[2:3], v162 offset1:65
	ds_read2_b32 v[4:5], v162 offset0:130 offset1:195
	ds_read2_b32 v[8:9], v0 offset0:134 offset1:199
	s_waitcnt lgkmcnt(0)
	v_cvt_pk_bf16_f32 v2, v2, v3
	v_cvt_pk_bf16_f32 v3, v4, v5
	ds_read2_b32 v[4:5], v0 offset0:4 offset1:69
	s_waitcnt lgkmcnt(0)
	v_cvt_pk_bf16_f32 v4, v4, v5
	v_cvt_pk_bf16_f32 v5, v8, v9
	v_add_u32_e32 v8, s4, v161
	v_ashrrev_i32_e32 v9, 31, v8
	v_lshlrev_b64 v[8:9], 11, v[8:9]
	v_lshl_add_u64 v[6:7], v[6:7], 0, v[8:9]
	v_subrev_u32_e32 v240, s94, v6
	v_bfe_u32 v241, v240, 6, 5
	v_and_b32_e32 v242, 63, v240
	v_lshl_or_b32 v242, v241, 10, v242
	v_bfe_u32 v241, v240, 11, 4
	v_lshl_or_b32 v242, v241, 6, v242
	v_and_b32_e32 v241, 0x7fff, v240
	v_sub_u32_e32 v242, v242, v241
	v_ashrrev_i32_e32 v243, 31, v242
	v_lshl_add_u64 v[240:241], v[6:7], 0, v[242:243]
	flat_store_dwordx4 v[240:241], v[2:5]

	.amdhsa_kernel _Z14fwd_megakernel6Params
		.amdhsa_group_segment_fixed_size 79888
		.amdhsa_private_segment_fixed_size 0
		.amdhsa_kernarg_size 408
		.amdhsa_user_sgpr_count 2
		.amdhsa_user_sgpr_dispatch_ptr 0
		.amdhsa_user_sgpr_queue_ptr 0
		.amdhsa_user_sgpr_kernarg_segment_ptr 1
		.amdhsa_user_sgpr_dispatch_id 0
		.amdhsa_user_sgpr_kernarg_preload_length 0
		.amdhsa_user_sgpr_kernarg_preload_offset 0
		.amdhsa_user_sgpr_private_segment_size 0
		.amdhsa_uses_dynamic_stack 0
		.amdhsa_enable_private_segment 0
		.amdhsa_system_sgpr_workgroup_id_x 1
		.amdhsa_system_sgpr_workgroup_id_y 0
		.amdhsa_system_sgpr_workgroup_id_z 0
		.amdhsa_system_sgpr_workgroup_info 0
		.amdhsa_system_vgpr_workitem_id 2
		.amdhsa_next_free_vgpr 256
		.amdhsa_next_free_sgpr 102
		.amdhsa_accum_offset 256
		.amdhsa_reserve_vcc 1
		.amdhsa_float_round_mode_32 0
		.amdhsa_float_round_mode_16_64 0
		.amdhsa_float_denorm_mode_32 3
		.amdhsa_float_denorm_mode_16_64 3
		.amdhsa_dx10_clamp 1
		.amdhsa_ieee_mode 1
		.amdhsa_fp16_overflow 0
		.amdhsa_tg_split 0
		.amdhsa_exception_fp_ieee_invalid_op 0
		.amdhsa_exception_fp_denorm_src 0
		.amdhsa_exception_fp_ieee_div_zero 0
		.amdhsa_exception_fp_ieee_overflow 0
		.amdhsa_exception_fp_ieee_underflow 0
		.amdhsa_exception_fp_ieee_inexact 0
		.amdhsa_exception_int_div_zero 0
	.end_amdhsa_kernel

amdhsa.kernels:
  - .agpr_count:     0
    .args:
      - .offset:         0
        .size:           152
        .value_kind:     by_value
      - .offset:         152
        .size:           4
        .value_kind:     hidden_block_count_x
      - .offset:         156
        .size:           4
        .value_kind:     hidden_block_count_y
      - .offset:         160
        .size:           4
        .value_kind:     hidden_block_count_z
      - .offset:         164
        .size:           2
        .value_kind:     hidden_group_size_x
      - .offset:         166
        .size:           2
        .value_kind:     hidden_group_size_y
      - .offset:         168
        .size:           2
        .value_kind:     hidden_group_size_z
      - .offset:         170
        .size:           2
        .value_kind:     hidden_remainder_x
      - .offset:         172
        .size:           2
        .value_kind:     hidden_remainder_y
      - .offset:         174
        .size:           2
        .value_kind:     hidden_remainder_z
      - .offset:         192
        .size:           8
        .value_kind:     hidden_global_offset_x
      - .offset:         200
        .size:           8
        .value_kind:     hidden_global_offset_y
      - .offset:         208
        .size:           8
        .value_kind:     hidden_global_offset_z
      - .offset:         216
        .size:           2
        .value_kind:     hidden_grid_dims
      - .offset:         240
        .size:           8
        .value_kind:     hidden_multigrid_sync_arg
    .group_segment_fixed_size: 79888
    .kernarg_segment_align: 8
    .kernarg_segment_size: 408
    .language:       OpenCL C
    .language_version:
      - 2
      - 0
    .max_flat_workgroup_size: 256
    .name:           _Z14fwd_megakernel6Params
    .private_segment_fixed_size: 0
    .sgpr_count:     108
    .sgpr_spill_count: 147
    .symbol:         _Z14fwd_megakernel6Params.kd
    .uniform_work_group_size: 1
    .uses_dynamic_stack: false
    .vgpr_count:     256
    .vgpr_spill_count: 0
    .wavefront_size: 64
